# baseline (speedup 1.0000x reference)
; __device__ __forceinline__ void gemm_mainloop_256(const u16* __restrict__ A, const u16* __restrict__ Bt,
;                                                   f32x16 (&acc)[4][2], char* smem) {
;   const int tid = tid_opaque(), lane = tid & 63, w = tid >> 6, wm = w >> 1, wn = w & 1;
;   u16* As = (u16*)smem;
;   u16* Bs = As + 256 * 72;
;   const int r0 = tid >> 3, kc = (tid & 7) * 8;
;   const u16* ga = A + (long)r0 * 1024 + kc;
;   const u16* gb = Bt + (long)r0 * 1024 + kc;
; #pragma unroll
;   for (int i = 0; i < 4; ++i)
; #pragma unroll
;     for (int j = 0; j < 2; ++j)
; #pragma unroll
;       for (int r = 0; r < 16; ++r) acc[i][j][r] = 0.f;
;   u32x4 ra[8], rb4[4];
;   auto gl = [&](int kt) {
; #pragma unroll
;     for (int i = 0; i < 8; ++i) ra[i] = *(const u32x4*)(ga + i * 32768 + kt * 64);
; #pragma unroll
;     for (int i = 0; i < 4; ++i) rb4[i] = *(const u32x4*)(gb + i * 32768 + kt * 64);
;   };
;   const int wofs = r0 * 72 + kc;
;   const int aofs = (wm * 128 + (lane & 31)) * 72 + (lane >> 5) * 8;
;   const int bofs = (wn * 64 + (lane & 31)) * 72 + (lane >> 5) * 8;
;   gl(0);
; __device__ __forceinline__ void phaseA(const P& p, int l, char* smem, unsigned* ctr) {
;     ...
;       const int g = n / 104, r = n % 104;
;       const int nt = (g < 4) ? (r >> 2) : r;
;       const int mt = 17 * xq + 4 * g + ((g < 4) ? (r & 3) : 0);
;       f32x16 acc[4][2];
;       gemm_mainloop_256(p.xn + (long)mt * 256 * 1024, p.wt_in + ((long)l * NIN + nt * 128) * 1024, acc, smem);
.LBB0_114:
	s_or_b64 exec, exec, s[0:1]
	s_waitcnt lgkmcnt(0)
	s_barrier
	ds_read2_b32 v[2:3], v245 offset0:240 offset1:243
	s_movk_i32 s0, 0x1b9
	s_waitcnt lgkmcnt(0)
	v_cmp_lt_i32_e32 vcc, s0, v2
	v_readfirstlane_b32 s2, v2
	v_readfirstlane_b32 s6, v3
	s_mov_b64 s[0:1], -1
	s_cbranch_vccnz .LBB0_132
	s_barrier
	s_and_saveexec_b64 s[0:1], s[4:5]
	s_add_i32 s7, s2, 1
	v_mov_b32_e32 v2, s7
	ds_write_b32 v131, v2 offset:57280
	s_or_b64 exec, exec, s[0:1]
	s_mul_hi_i32 s0, s2, 0x4ec4ec4f
	s_lshr_b32 s1, s0, 31
	s_ashr_i32 s0, s0, 5
	s_add_i32 s0, s0, s1
	s_mul_i32 s1, s0, 0x68
	s_sub_i32 s1, s2, s1
	s_mul_i32 s8, s6, 17
	s_lshl_b32 s0, s0, 2
	s_ashr_i32 s7, s1, 2
	s_add_i32 s0, s0, s8
	s_and_b32 s8, s1, 3
	s_cmpk_lt_i32 s2, 0x1a0
	s_cselect_b32 s7, s7, s1
	s_cselect_b32 s1, s8, 0
	s_add_i32 s8, s0, s1
	s_ashr_i32 s9, s8, 31
	s_lshl_b64 s[0:1], s[8:9], 19
	s_add_u32 s0, s60, s0
	s_addc_u32 s1, s61, s1
	s_lshl_b32 s94, s7, 7
	s_ashr_i32 s95, s94, 31
	v_mov_b32_e32 v8, v198
	s_lshl_b64 s[20:21], s[94:95], 11
	s_add_u32 s20, s50, s20
	v_ashrrev_i32_e32 v2, 3, v8
	v_lshlrev_b32_e32 v3, 3, v8
	v_and_b32_e32 v9, 56, v3
	v_ashrrev_i32_e32 v3, 31, v2
	s_addc_u32 s21, s51, s21
	v_lshlrev_b64 v[4:5], 11, v[2:3]
	v_lshl_add_u64 v[6:7], s[20:21], 0, v[4:5]
	v_lshl_add_u64 v[4:5], s[0:1], 0, v[4:5]
	v_lshlrev_b32_e32 v130, 1, v9
	v_lshl_add_u64 v[184:185], v[4:5], 0, v[130:131]
	s_movk_i32 s0, 0x48
	v_lshl_add_u64 v[186:187], v[6:7], 0, v[130:131]
	v_mul_lo_u32 v6, v2, s0
	v_add_co_u32_e32 v2, vcc, s37, v184
	global_load_dwordx4 v[134:137], v[184:185], off
	s_nop 0
	v_addc_co_u32_e32 v3, vcc, 0, v185, vcc
	v_add_co_u32_e32 v4, vcc, s17, v184
	v_and_b32_e32 v7, 0xfffff9f, v8
	s_nop 0
	v_addc_co_u32_e32 v5, vcc, 0, v185, vcc
	global_load_dwordx4 v[142:145], v[2:3], off
	global_load_dwordx4 v[146:149], v[4:5], off
	v_add_co_u32_e32 v2, vcc, s19, v184
	v_and_b32_e32 v10, 0x5f, v8
	s_nop 0
	v_addc_co_u32_e32 v3, vcc, 0, v185, vcc
	v_add_co_u32_e32 v4, vcc, s23, v184
	v_add_lshl_u32 v133, v6, v9, 1
	s_nop 0
	v_addc_co_u32_e32 v5, vcc, 0, v185, vcc
	global_load_dwordx4 v[150:153], v[2:3], off
	global_load_dwordx4 v[154:157], v[4:5], off
	v_add_co_u32_e32 v2, vcc, s3, v184
	s_nop 1
	v_addc_co_u32_e32 v3, vcc, 0, v185, vcc
	v_add_co_u32_e32 v4, vcc, s15, v184
	s_nop 1
	v_addc_co_u32_e32 v5, vcc, 0, v185, vcc
	global_load_dwordx4 v[158:161], v[2:3], off
	global_load_dwordx4 v[162:165], v[4:5], off
	v_add_co_u32_e32 v2, vcc, 0x70000, v184
	s_nop 1
	v_addc_co_u32_e32 v3, vcc, 0, v185, vcc
	global_load_dwordx4 v[166:169], v[2:3], off
	global_load_dwordx4 v[138:141], v[186:187], off
	v_add_co_u32_e32 v2, vcc, s37, v186
	s_nop 1
	v_addc_co_u32_e32 v3, vcc, 0, v187, vcc
	v_add_co_u32_e32 v4, vcc, s17, v186
	s_nop 1
	v_addc_co_u32_e32 v5, vcc, 0, v187, vcc
	global_load_dwordx4 v[170:173], v[2:3], off
	global_load_dwordx4 v[174:177], v[4:5], off
	v_add_co_u32_e32 v2, vcc, 0x30000, v186
	s_nop 1
	v_addc_co_u32_e32 v3, vcc, 0, v187, vcc
	global_load_dwordx4 v[178:181], v[2:3], off
	v_lshrrev_b32_e32 v2, 1, v8
	v_and_b32_e32 v2, 16, v2
	v_mad_u64_u32 v[182:183], s[0:1], v7, s89, v[2:3]
	v_mad_u32_u24 v130, v10, s89, v2
	v_mov_b32_e32 v2, 0
	s_mov_b64 s[0:1], 0
	v_mov_b32_e32 v3, v2
	v_mov_b32_e32 v4, v2
	v_mov_b32_e32 v5, v2
	v_mov_b32_e32 v6, v2
	v_mov_b32_e32 v7, v2
	v_mov_b32_e32 v8, v2
	v_mov_b32_e32 v9, v2
	v_mov_b32_e32 v10, v2
	v_mov_b32_e32 v11, v2
	v_mov_b32_e32 v12, v2
	v_mov_b32_e32 v13, v2
	v_mov_b32_e32 v14, v2
	v_mov_b32_e32 v15, v2
	v_mov_b32_e32 v16, v2
	v_mov_b32_e32 v17, v2
	v_mov_b32_e32 v18, v2
	v_mov_b32_e32 v19, v2
	v_mov_b32_e32 v20, v2
	v_mov_b32_e32 v21, v2
	v_mov_b32_e32 v22, v2
	v_mov_b32_e32 v23, v2
	v_mov_b32_e32 v24, v2
	v_mov_b32_e32 v25, v2
	v_mov_b32_e32 v26, v2
	v_mov_b32_e32 v27, v2
	v_mov_b32_e32 v28, v2
	v_mov_b32_e32 v29, v2
	v_mov_b32_e32 v30, v2
	v_mov_b32_e32 v31, v2
	v_mov_b32_e32 v32, v2
	v_mov_b32_e32 v33, v2
	v_mov_b32_e32 v34, v2
	v_mov_b32_e32 v35, v2
	v_mov_b32_e32 v36, v2
	v_mov_b32_e32 v37, v2
	v_mov_b32_e32 v38, v2
	v_mov_b32_e32 v39, v2
	v_mov_b32_e32 v40, v2
	v_mov_b32_e32 v41, v2
	v_mov_b32_e32 v42, v2
	v_mov_b32_e32 v43, v2
	v_mov_b32_e32 v44, v2
	v_mov_b32_e32 v45, v2
	v_mov_b32_e32 v46, v2
	v_mov_b32_e32 v47, v2
	v_mov_b32_e32 v48, v2
	v_mov_b32_e32 v49, v2
	v_mov_b32_e32 v50, v2
	v_mov_b32_e32 v51, v2
	v_mov_b32_e32 v52, v2
	v_mov_b32_e32 v53, v2
	v_mov_b32_e32 v54, v2
	v_mov_b32_e32 v55, v2
	v_mov_b32_e32 v56, v2
	v_mov_b32_e32 v57, v2
	v_mov_b32_e32 v58, v2
	v_mov_b32_e32 v59, v2
	v_mov_b32_e32 v60, v2
	v_mov_b32_e32 v61, v2
	v_mov_b32_e32 v62, v2
	v_mov_b32_e32 v63, v2
	v_mov_b32_e32 v64, v2
	v_mov_b32_e32 v65, v2
	v_mov_b32_e32 v66, v2
	v_mov_b32_e32 v67, v2
	v_mov_b32_e32 v68, v2
	v_mov_b32_e32 v69, v2
	v_mov_b32_e32 v70, v2
	v_mov_b32_e32 v71, v2
	v_mov_b32_e32 v72, v2
	v_mov_b32_e32 v73, v2
	v_mov_b32_e32 v74, v2
	v_mov_b32_e32 v75, v2
	v_mov_b32_e32 v76, v2
	v_mov_b32_e32 v77, v2
	v_mov_b32_e32 v78, v2
	v_mov_b32_e32 v79, v2
	v_mov_b32_e32 v80, v2
	v_mov_b32_e32 v81, v2
	v_mov_b32_e32 v82, v2
	v_mov_b32_e32 v83, v2
	v_mov_b32_e32 v84, v2
	v_mov_b32_e32 v85, v2
	v_mov_b32_e32 v86, v2
	v_mov_b32_e32 v87, v2
	v_mov_b32_e32 v88, v2
	v_mov_b32_e32 v89, v2
	v_mov_b32_e32 v90, v2
	v_mov_b32_e32 v91, v2
	v_mov_b32_e32 v92, v2
	v_mov_b32_e32 v93, v2
	v_mov_b32_e32 v94, v2
	v_mov_b32_e32 v95, v2
	v_mov_b32_e32 v96, v2
	v_mov_b32_e32 v97, v2
	v_mov_b32_e32 v98, v2
	v_mov_b32_e32 v99, v2
	v_mov_b32_e32 v100, v2
	v_mov_b32_e32 v101, v2
	v_mov_b32_e32 v102, v2
	v_mov_b32_e32 v103, v2
	v_mov_b32_e32 v104, v2
	v_mov_b32_e32 v105, v2
	v_mov_b32_e32 v106, v2
	v_mov_b32_e32 v107, v2
	v_mov_b32_e32 v108, v2
	v_mov_b32_e32 v109, v2
	v_mov_b32_e32 v110, v2
	v_mov_b32_e32 v111, v2
	v_mov_b32_e32 v112, v2
	v_mov_b32_e32 v113, v2
	v_mov_b32_e32 v114, v2
	v_mov_b32_e32 v115, v2
	v_mov_b32_e32 v116, v2
	v_mov_b32_e32 v117, v2
	v_mov_b32_e32 v118, v2
	v_mov_b32_e32 v119, v2
	v_mov_b32_e32 v120, v2
	v_mov_b32_e32 v121, v2
	v_mov_b32_e32 v122, v2
	v_mov_b32_e32 v123, v2
	v_mov_b32_e32 v124, v2
	v_mov_b32_e32 v125, v2
	v_mov_b32_e32 v126, v2
	v_mov_b32_e32 v127, v2
	v_mov_b32_e32 v128, v2
	v_mov_b32_e32 v129, v2
	.p2align	6

; template <int DQK, int MODE> ...
;     ...
;   auto lstore = [&](const TRegs& R, int st) {
;     u16* Ks = lds + st * STG;
;     u16* Vs = Ks + KT;
; #pragma unroll
;     for (int i = 0; i < NKL; ++i) {
;       int c = tid + i * 256;
;       int row = c / KCH, cc = c % KCH;
;       *(u32x4*)(Ks + row * KST + cc * 8) = R.k[i];
;     }
; #pragma unroll
;     for (int i = 0; i < 2; ++i) {
;       int c = tid + i * 256;
;       int d = c >> 3, cc = c & 7;
;       u32x2 lo = {R.v[i].x, R.v[i].y}, hi = {R.v[i].z, R.v[i].w};
;       *(u32x2*)(Vs + d * VST + cc * 8) = lo;
;       *(u32x2*)(Vs + d * VST + cc * 8 + 4) = hi;
;     }
;     ...
;   f32x16 O[2];
; #pragma unroll
;   for (int du = 0; du < 2; ++du)
; #pragma unroll
;     for (int r = 0; r < 16; ++r) O[du][r] = 0.f;
;   float m_run = 0.f, lsum = 0.f;
;   bool first = true;
;   float carry = active ? 1.f : 0.f;
;   const int dir = (MODE == 2) ? -1 : 1;
;   const int jstart = (MODE == 2) ? jhi : jlo;
;   const int ntile = jhi - jlo + 1;
;     ...
;   {
;     TRegs R0, R1;
;     gload(R0, jstart);
;     if (ntile > 1) gload(R1, jstart + dir);
.LBB0_985:
	v_lshlrev_b32_e32 v176, 3, v15
	v_mov_b32_e32 v49, 0
	s_cmp_lt_i32 s4, 0xfff00000
	v_mov_b32_e32 v48, 0
	v_mov_b32_e32 v47, 0
	v_mov_b32_e32 v46, 0
	v_mov_b32_e32 v45, 0
	v_mov_b32_e32 v44, 0
	v_mov_b32_e32 v43, 0
	v_mov_b32_e32 v42, 0
	v_mov_b32_e32 v41, 0
	v_mov_b32_e32 v40, 0
	v_mov_b32_e32 v39, 0
	v_mov_b32_e32 v38, 0
	v_mov_b32_e32 v37, 0
	v_mov_b32_e32 v36, 0
	v_mov_b32_e32 v35, 0
	v_mov_b32_e32 v34, 0
	v_mov_b32_e32 v33, 0
	v_mov_b32_e32 v32, 0
	v_mov_b32_e32 v31, 0
	v_mov_b32_e32 v30, 0
	v_mov_b32_e32 v29, 0
	v_mov_b32_e32 v28, 0
	v_mov_b32_e32 v27, 0
	v_mov_b32_e32 v26, 0
	v_mov_b32_e32 v25, 0
	v_mov_b32_e32 v24, 0
	v_mov_b32_e32 v23, 0
	v_mov_b32_e32 v22, 0
	v_mov_b32_e32 v21, 0
	v_mov_b32_e32 v20, 0
	v_mov_b32_e32 v19, 0
	v_mov_b32_e32 v18, 0
	v_mov_b32_e32 v177, 0
	s_cbranch_scc1 .LBB0_1002
	v_lshl_add_u64 v[178:179], v[4:5], 1, s[16:17]
	v_ashrrev_i32_e32 v5, 7, v14
	v_cndmask_b32_e64 v5, 0, v5, s[0:1]
	v_add_u32_e32 v199, s3, v5
	v_max_i32_e32 v5, 0x100000, v199
	s_movk_i32 s0, 0xd0
	v_add_u32_e32 v200, 0xfff00000, v5
	v_mul_lo_u32 v5, v171, s0
	v_lshl_add_u32 v201, v4, 1, v5
	v_mul_lo_u32 v4, v173, s0
	v_lshl_add_u32 v202, v6, 1, v4
	v_mul_lo_u32 v4, v175, s0
	v_lshl_add_u32 v203, v10, 1, v4
	v_lshrrev_b32_e32 v4, 3, v14
	s_movk_i32 s4, 0x98
	v_mad_u64_u32 v[184:185], s[0:1], v4, s4, v[2:3]
	v_lshrrev_b32_e32 v4, 3, v16
	v_mad_u64_u32 v[186:187], s[0:1], v4, s4, v[2:3]
	v_lshlrev_b32_e32 v2, 1, v176
	v_mul_u32_u24_e32 v4, 0x68, v172
	v_lshl_add_u32 v185, v4, 1, v2
	v_sub_u32_e32 v2, v2, v176
	v_mul_u32_u24_e32 v4, 0x4c, v172
	s_mov_b32 s13, s37
	v_lshl_add_u32 v187, v4, 1, v2
	s_lshl_b64 s[0:1], s[12:13], 13
	v_and_b32_e32 v2, 7, v14
	v_lshl_or_b32 v4, v2, 4, s0
	v_mov_b32_e32 v5, s1
	v_lshl_add_u64 v[180:181], v[6:7], 1, s[16:17]
	v_lshl_add_u64 v[6:7], v[8:9], 1, v[4:5]
	v_lshl_add_u64 v[4:5], v[12:13], 1, v[4:5]
	v_mov_b32_e32 v16, v3
	v_mov_b32_e32 v17, v3
	v_lshl_add_u64 v[182:183], v[10:11], 1, s[16:17]
	v_lshl_add_u64 v[188:189], s[14:15], 0, v[6:7]
	v_lshl_add_u64 v[190:191], s[14:15], 0, v[4:5]
	v_mov_b32_e32 v2, v3
	v_mov_b32_e32 v4, v3
	v_mov_b32_e32 v5, v3
	v_mov_b32_e32 v6, v3
	v_mov_b32_e32 v7, v3
	v_mov_b32_e32 v8, v3
	v_mov_b32_e32 v9, v3
	v_mov_b32_e32 v10, v3
	v_mov_b32_e32 v11, v3
	v_mov_b32_e32 v12, v3
	v_mov_b32_e32 v13, v3
	v_mov_b32_e32 v14, v3
	v_mov_b32_e32 v15, v3
	v_mov_b64_e32 v[32:33], v[16:17]
	v_mov_b64_e32 v[48:49], v[16:17]
	s_mov_b32 s3, 3
	s_lshl_b32 s4, s12, 6
	s_mov_b64 s[0:1], -1
	v_mov_b32_e32 v177, 0
	s_xor_b64 s[14:15], vcc, -1
	v_mov_b64_e32 v[30:31], v[14:15]
	v_mov_b64_e32 v[28:29], v[12:13]
	v_mov_b64_e32 v[26:27], v[10:11]
	v_mov_b64_e32 v[24:25], v[8:9]
	v_mov_b64_e32 v[22:23], v[6:7]
	v_mov_b64_e32 v[20:21], v[4:5]
	v_mov_b64_e32 v[18:19], v[2:3]
	v_mov_b64_e32 v[46:47], v[14:15]
	v_mov_b64_e32 v[44:45], v[12:13]
	v_mov_b64_e32 v[42:43], v[10:11]
	v_mov_b64_e32 v[40:41], v[8:9]
	v_mov_b64_e32 v[38:39], v[6:7]
	v_mov_b64_e32 v[36:37], v[4:5]
	v_mov_b64_e32 v[34:35], v[2:3]
	v_mov_b32_e32 v2, 0
	v_mov_b64_e32 v[228:229], 0
	v_mov_b64_e32 v[230:231], 0
	v_mov_b64_e32 v[232:233], 0
	v_mov_b64_e32 v[234:235], 0
	v_mov_b64_e32 v[236:237], 0
	v_mov_b64_e32 v[238:239], 0
	v_mov_b64_e32 v[240:241], 0
	v_mov_b64_e32 v[242:243], 0
	s_waitcnt vmcnt(0)
	v_add_u32_e32 v226, 0x3400, v184
	ds_write_b128 v201, v[106:109]
	ds_write_b128 v202, v[110:113]
	ds_write_b128 v203, v[114:117]
	ds_write2_b64 v226, v[118:119], v[120:121] offset1:1
	v_add_u32_e32 v226, 0x3400, v186
	ds_write2_b64 v226, v[130:131], v[132:133] offset1:1
	s_branch .LBB0_990
	.p2align	6

; template <bool ROWRMS>
; __device__ __forceinline__ void gemm_mainloop(const u16* __restrict__ A, int lda, const u16* __restrict__ Bt, int ldb,
;                                               int K, f32x16 (&acc)[2][2], char* smem, float* rs) {
;   const int tid = tid_opaque(), lane = tid & 63, w = tid >> 6, wm = w >> 1, wn = w & 1;
;   u16* As = (u16*)smem;
;   u16* Bs = As + 128 * 72;
;   const int r0 = tid >> 3, kc = (tid & 7) * 8;
;   const u16* ga = A + (long)r0 * lda + kc;
;   const u16* gb = Bt + (long)r0 * ldb + kc;
;   const long a32 = 32L * lda, b32 = 32L * ldb;
;   float ss[4] = {0.f, 0.f, 0.f, 0.f};
; #pragma unroll
;   for (int i = 0; i < 2; ++i)
; #pragma unroll
;     for (int j = 0; j < 2; ++j)
; #pragma unroll
;       for (int r = 0; r < 16; ++r) acc[i][j][r] = 0.f;
;   const int nk = K >> 6;
;   const int wofs = r0 * 72 + kc;
;   const int aofs = (wm * 64 + (lane & 31)) * 72 + (lane >> 5) * 8;
;   const int bofs = (wn * 64 + (lane & 31)) * 72 + (lane >> 5) * 8;
;   auto gl = [&](GRegs& R, int kt) {
;     const int ko = kt * 64;
; #pragma unroll
;     for (int i = 0; i < 4; ++i) {
;       R.a[i] = *(const u32x4*)(ga + i * a32 + ko);
;       R.b[i] = *(const u32x4*)(gb + i * b32 + ko);
;     }
;   };
; __device__ __forceinline__ void phaseD(const P& p, int l, char* smem, unsigned* ctr) {
;     ...
;   run_xcd_queues(ctr, 272, 4, smem, [&](int xq, int n) {
;       const int mt = 34 * xq + (n >> 3), nt = n & 7;
;       f32x16 acc[2][2];
;       gemm_mainloop<false>(p.xn + (long)mt * 128 * 1024, 1024, p.wt_out + ((long)l * 1024 + nt * 128) * 1024, 1024, 1024, acc, smem, nullptr);
.LBB0_1126:
	s_or_b64 exec, exec, s[12:13]
	s_waitcnt lgkmcnt(0)
	s_barrier
	ds_read2_b32 v[2:3], v146 offset0:240 offset1:243
	s_movk_i32 s12, 0x10f
	s_waitcnt lgkmcnt(0)
	v_cmp_lt_i32_e32 vcc, s12, v2
	v_readfirstlane_b32 s14, v2
	v_readfirstlane_b32 s16, v3
	s_mov_b64 s[12:13], -1
	s_cbranch_vccnz .LBB0_1135
	s_barrier
	s_and_saveexec_b64 s[12:13], s[4:5]
	s_add_i32 s15, s14, 1
	v_mov_b32_e32 v2, s15
	ds_write_b32 v67, v2 offset:57280
	s_or_b64 exec, exec, s[12:13]
	s_mul_i32 s12, s16, 34
	s_ashr_i32 s13, s14, 3
	s_add_i32 s12, s12, s13
	s_ashr_i32 s13, s12, 31
	s_and_b32 s17, s14, 7
	s_lshl_b64 s[14:15], s[12:13], 18
	s_add_u32 s14, s60, s14
	v_mov_b32_e32 v20, v198
	s_addc_u32 s15, s61, s15
	s_lshl_b32 s13, s17, 18
	s_add_u32 s34, s52, s13
	v_ashrrev_i32_e32 v2, 3, v20
	v_lshlrev_b32_e32 v3, 3, v20
	v_and_b32_e32 v21, 56, v3
	v_ashrrev_i32_e32 v3, 31, v2
	s_addc_u32 s35, s53, 0
	v_lshlrev_b64 v[4:5], 11, v[2:3]
	v_lshl_add_u64 v[136:137], s[34:35], 0, v[4:5]
	v_lshlrev_b32_e32 v66, 1, v21
	v_lshl_add_u64 v[6:7], v[136:137], 0, v[66:67]
	v_lshl_add_u64 v[138:139], s[14:15], 0, v[4:5]
	v_add_co_u32_e32 v8, vcc, s3, v6
	v_lshl_add_u64 v[4:5], v[138:139], 0, v[66:67]
	s_nop 0
	v_addc_co_u32_e32 v9, vcc, 0, v7, vcc
	v_add_co_u32_e32 v10, vcc, s3, v4
	s_mov_b32 s14, 0xfffffc0
	s_nop 0
	v_addc_co_u32_e32 v11, vcc, 0, v5, vcc
	v_add_co_u32_e32 v12, vcc, s18, v6
	v_and_b32_e32 v3, 0x5f, v20
	s_nop 0
	v_addc_co_u32_e32 v13, vcc, 0, v7, vcc
	v_add_co_u32_e32 v14, vcc, s18, v4
	s_mov_b32 s13, 0
	s_nop 0
	v_addc_co_u32_e32 v15, vcc, 0, v5, vcc
	v_add_co_u32_e32 v16, vcc, s19, v6
	s_nop 1
	v_addc_co_u32_e32 v17, vcc, 0, v7, vcc
	v_add_co_u32_e32 v18, vcc, s19, v4
	s_nop 1
	v_addc_co_u32_e32 v19, vcc, 0, v5, vcc
	global_load_dwordx4 v[126:129], v[8:9], off offset:128
	global_load_dwordx4 v[130:133], v[8:9], off
	global_load_dwordx4 v[118:121], v[10:11], off offset:128
	global_load_dwordx4 v[122:125], v[10:11], off
	global_load_dwordx4 v[110:113], v[12:13], off offset:128
	global_load_dwordx4 v[114:117], v[12:13], off
	global_load_dwordx4 v[102:105], v[14:15], off offset:128
	global_load_dwordx4 v[106:109], v[14:15], off
	global_load_dwordx4 v[94:97], v[16:17], off offset:128
	global_load_dwordx4 v[98:101], v[16:17], off
	global_load_dwordx4 v[86:89], v[18:19], off offset:128
	global_load_dwordx4 v[90:93], v[18:19], off
	global_load_dwordx4 v[70:73], v[6:7], off offset:128
	global_load_dwordx4 v[74:77], v[6:7], off
	global_load_dwordx4 v[78:81], v[4:5], off offset:128
	global_load_dwordx4 v[82:85], v[4:5], off
	v_lshrrev_b32_e32 v4, 1, v20
	v_and_b32_e32 v5, 31, v20
	v_and_or_b32 v5, v4, s14, v5
	s_movk_i32 s14, 0x48
	v_mul_lo_u32 v2, v2, s14
	v_add_lshl_u32 v69, v2, v21, 1
	v_and_b32_e32 v2, 16, v4
	v_mad_u64_u32 v[140:141], s[14:15], v5, s20, v[2:3]
	v_mad_u32_u24 v141, v3, s20, v2
	v_and_b32_e32 v2, 7, v20
	v_lshlrev_b32_e32 v66, 4, v2
	v_mov_b32_e32 v2, 0
	v_mov_b32_e32 v3, v2
	v_mov_b32_e32 v4, v2
	v_mov_b32_e32 v5, v2
	v_mov_b32_e32 v6, v2
	v_mov_b32_e32 v7, v2
	v_mov_b32_e32 v8, v2
	v_mov_b32_e32 v9, v2
	v_mov_b32_e32 v10, v2
	v_mov_b32_e32 v11, v2
	v_mov_b32_e32 v12, v2
	v_mov_b32_e32 v13, v2
	v_mov_b32_e32 v14, v2
	v_mov_b32_e32 v15, v2
	v_mov_b32_e32 v16, v2
	v_mov_b32_e32 v17, v2
	v_mov_b32_e32 v18, v2
	v_mov_b32_e32 v19, v2
	v_mov_b32_e32 v20, v2
	v_mov_b32_e32 v21, v2
	v_mov_b32_e32 v22, v2
	v_mov_b32_e32 v23, v2
	v_mov_b32_e32 v24, v2
	v_mov_b32_e32 v25, v2
	v_mov_b32_e32 v26, v2
	v_mov_b32_e32 v27, v2
	v_mov_b32_e32 v28, v2
	v_mov_b32_e32 v29, v2
	v_mov_b32_e32 v30, v2
	v_mov_b32_e32 v31, v2
	v_mov_b32_e32 v32, v2
	v_mov_b32_e32 v33, v2
	v_mov_b32_e32 v34, v2
	v_mov_b32_e32 v35, v2
	v_mov_b32_e32 v36, v2
	v_mov_b32_e32 v37, v2
	v_mov_b32_e32 v38, v2
	v_mov_b32_e32 v39, v2
	v_mov_b32_e32 v40, v2
	v_mov_b32_e32 v41, v2
	v_mov_b32_e32 v42, v2
	v_mov_b32_e32 v43, v2
	v_mov_b32_e32 v44, v2
	v_mov_b32_e32 v45, v2
	v_mov_b32_e32 v46, v2
	v_mov_b32_e32 v47, v2
	v_mov_b32_e32 v48, v2
	v_mov_b32_e32 v49, v2
	v_mov_b32_e32 v50, v2
	v_mov_b32_e32 v51, v2
	v_mov_b32_e32 v52, v2
	v_mov_b32_e32 v53, v2
	v_mov_b32_e32 v54, v2
	v_mov_b32_e32 v55, v2
	v_mov_b32_e32 v56, v2
	v_mov_b32_e32 v57, v2
	v_mov_b32_e32 v58, v2
	v_mov_b32_e32 v59, v2
	v_mov_b32_e32 v60, v2
	v_mov_b32_e32 v61, v2
	v_mov_b32_e32 v62, v2
	v_mov_b32_e32 v63, v2
	v_mov_b32_e32 v64, v2
	v_mov_b32_e32 v65, v2
	s_branch .LBB0_1131
	.p2align	6

; __device__ __forceinline__ void gemm_mainloop_256(const u16* __restrict__ A, const u16* __restrict__ Bt,
;                                                   f32x16 (&acc)[4][2], char* smem) {
;   const int tid = tid_opaque(), lane = tid & 63, w = tid >> 6, wm = w >> 1, wn = w & 1;
;   u16* As = (u16*)smem;
;   u16* Bs = As + 256 * 72;
;   const int r0 = tid >> 3, kc = (tid & 7) * 8;
;   const u16* ga = A + (long)r0 * 1024 + kc;
;   const u16* gb = Bt + (long)r0 * 1024 + kc;
; #pragma unroll
;   for (int i = 0; i < 4; ++i)
; #pragma unroll
;     for (int j = 0; j < 2; ++j)
; #pragma unroll
;       for (int r = 0; r < 16; ++r) acc[i][j][r] = 0.f;
;   u32x4 ra[8], rb4[4];
;   auto gl = [&](int kt) {
; #pragma unroll
;     for (int i = 0; i < 8; ++i) ra[i] = *(const u32x4*)(ga + i * 32768 + kt * 64);
; #pragma unroll
;     for (int i = 0; i < 4; ++i) rb4[i] = *(const u32x4*)(gb + i * 32768 + kt * 64);
;   };
;   const int wofs = r0 * 72 + kc;
;   const int aofs = (wm * 128 + (lane & 31)) * 72 + (lane >> 5) * 8;
;   const int bofs = (wn * 64 + (lane & 31)) * 72 + (lane >> 5) * 8;
;   gl(0);
; __device__ __forceinline__ void phaseA(const P& p, int l, char* smem, unsigned* ctr) {
;     ...
;       const int g = n / 104, r = n % 104;
;       const int nt = (g < 4) ? (r >> 2) : r;
;       const int mt = 17 * xq + 4 * g + ((g < 4) ? (r & 3) : 0);
;       f32x16 acc[4][2];
;       gemm_mainloop_256(p.xn + (long)mt * 256 * 1024, p.wt_in + ((long)l * NIN + nt * 128) * 1024, acc, smem);
.LBB0_1250:
	s_or_b64 exec, exec, s[0:1]
	s_waitcnt lgkmcnt(0)
	s_barrier
	ds_read2_b32 v[2:3], v245 offset0:240 offset1:243
	s_movk_i32 s0, 0x1b9
	s_waitcnt lgkmcnt(0)
	v_cmp_lt_i32_e32 vcc, s0, v2
	v_readfirstlane_b32 s2, v2
	v_readfirstlane_b32 s6, v3
	s_mov_b64 s[0:1], -1
	s_cbranch_vccnz .LBB0_1268
	s_barrier
	s_and_saveexec_b64 s[0:1], s[4:5]
	s_add_i32 s3, s2, 1
	v_mov_b32_e32 v2, s3
	ds_write_b32 v131, v2 offset:57280
	s_or_b64 exec, exec, s[0:1]
	s_mul_hi_i32 s0, s2, 0x4ec4ec4f
	s_lshr_b32 s1, s0, 31
	s_ashr_i32 s0, s0, 5
	s_add_i32 s0, s0, s1
	s_mul_i32 s1, s0, 0x68
	s_sub_i32 s1, s2, s1
	s_mul_i32 s7, s6, 17
	s_lshl_b32 s0, s0, 2
	s_ashr_i32 s3, s1, 2
	s_add_i32 s0, s0, s7
	s_and_b32 s8, s1, 3
	s_cmpk_lt_i32 s2, 0x1a0
	s_cselect_b32 s7, s3, s1
	s_cselect_b32 s1, s8, 0
	s_add_i32 s2, s0, s1
	s_ashr_i32 s3, s2, 31
	s_lshl_b64 s[0:1], s[2:3], 19
	s_add_u32 s0, s60, s0
	s_addc_u32 s1, s61, s1
	s_lshl_b32 s96, s7, 7
	s_ashr_i32 s97, s96, 31
	v_mov_b32_e32 v8, v198
	s_lshl_b64 s[8:9], s[96:97], 11
	s_add_u32 s8, s50, s8
	v_ashrrev_i32_e32 v2, 3, v8
	v_lshlrev_b32_e32 v3, 3, v8
	v_and_b32_e32 v9, 56, v3
	v_ashrrev_i32_e32 v3, 31, v2
	s_addc_u32 s9, s51, s9
	v_lshlrev_b64 v[4:5], 11, v[2:3]
	v_lshl_add_u64 v[6:7], s[8:9], 0, v[4:5]
	v_lshl_add_u64 v[4:5], s[0:1], 0, v[4:5]
	v_lshlrev_b32_e32 v130, 1, v9
	v_lshl_add_u64 v[184:185], v[4:5], 0, v[130:131]
	v_lshl_add_u64 v[4:5], v[6:7], 0, v[130:131]
	s_mov_b64 s[0:1], 0x680000
	v_lshl_add_u64 v[186:187], v[4:5], 0, s[0:1]
	s_movk_i32 s0, 0x48
	v_mul_lo_u32 v10, v2, s0
	v_add_co_u32_e32 v2, vcc, s95, v184
	s_mov_b32 s0, 0x680000
	s_nop 0
	v_addc_co_u32_e32 v3, vcc, 0, v185, vcc
	global_load_dwordx4 v[134:137], v[184:185], off
	global_load_dwordx4 v[138:141], v[2:3], off
	v_add_co_u32_e32 v2, vcc, s17, v184
	v_and_b32_e32 v11, 0xfffff9f, v8
	s_nop 0
	v_addc_co_u32_e32 v3, vcc, 0, v185, vcc
	v_add_co_u32_e32 v6, vcc, s19, v184
	v_and_b32_e32 v12, 0x5f, v8
	s_nop 0
	v_addc_co_u32_e32 v7, vcc, 0, v185, vcc
	global_load_dwordx4 v[146:149], v[2:3], off
	global_load_dwordx4 v[150:153], v[6:7], off
	v_add_co_u32_e32 v2, vcc, s33, v184
	v_add_lshl_u32 v133, v10, v9, 1
	s_nop 0
	v_addc_co_u32_e32 v3, vcc, 0, v185, vcc
	v_add_co_u32_e32 v6, vcc, s37, v184
	s_nop 1
	v_addc_co_u32_e32 v7, vcc, 0, v185, vcc
	global_load_dwordx4 v[154:157], v[2:3], off
	global_load_dwordx4 v[158:161], v[6:7], off
	v_add_co_u32_e32 v2, vcc, s15, v184
	s_nop 1
	v_addc_co_u32_e32 v3, vcc, 0, v185, vcc
	v_add_co_u32_e32 v6, vcc, s23, v184
	s_nop 1
	v_addc_co_u32_e32 v7, vcc, 0, v185, vcc
	global_load_dwordx4 v[162:165], v[2:3], off
	global_load_dwordx4 v[166:169], v[6:7], off
	v_add_co_u32_e32 v2, vcc, s0, v4
	s_mov_b32 s0, 0x690000
	s_nop 0
	v_addc_co_u32_e32 v3, vcc, 0, v5, vcc
	v_add_co_u32_e32 v6, vcc, s0, v4
	s_mov_b32 s0, 0x6a0000
	s_nop 0
	v_addc_co_u32_e32 v7, vcc, 0, v5, vcc
	global_load_dwordx4 v[142:145], v[2:3], off
	global_load_dwordx4 v[170:173], v[6:7], off
	v_add_co_u32_e32 v2, vcc, s0, v4
	s_nop 1
	v_addc_co_u32_e32 v3, vcc, 0, v5, vcc
	v_add_co_u32_e32 v4, vcc, 0x6b0000, v4
	s_nop 1
	v_addc_co_u32_e32 v5, vcc, 0, v5, vcc
	global_load_dwordx4 v[174:177], v[2:3], off
	global_load_dwordx4 v[178:181], v[4:5], off
	v_lshrrev_b32_e32 v2, 1, v8
	v_and_b32_e32 v2, 16, v2
	v_mad_u64_u32 v[182:183], s[0:1], v11, s88, v[2:3]
	v_mad_u32_u24 v130, v12, s88, v2
	v_mov_b32_e32 v2, 0
	s_mov_b64 s[0:1], 0
	v_mov_b32_e32 v3, v2
	v_mov_b32_e32 v4, v2
	v_mov_b32_e32 v5, v2
	v_mov_b32_e32 v6, v2
	v_mov_b32_e32 v7, v2
	v_mov_b32_e32 v8, v2
	v_mov_b32_e32 v9, v2
	v_mov_b32_e32 v10, v2
	v_mov_b32_e32 v11, v2
	v_mov_b32_e32 v12, v2
	v_mov_b32_e32 v13, v2
	v_mov_b32_e32 v14, v2
	v_mov_b32_e32 v15, v2
	v_mov_b32_e32 v16, v2
	v_mov_b32_e32 v17, v2
	v_mov_b32_e32 v18, v2
	v_mov_b32_e32 v19, v2
	v_mov_b32_e32 v20, v2
	v_mov_b32_e32 v21, v2
	v_mov_b32_e32 v22, v2
	v_mov_b32_e32 v23, v2
	v_mov_b32_e32 v24, v2
	v_mov_b32_e32 v25, v2
	v_mov_b32_e32 v26, v2
	v_mov_b32_e32 v27, v2
	v_mov_b32_e32 v28, v2
	v_mov_b32_e32 v29, v2
	v_mov_b32_e32 v30, v2
	v_mov_b32_e32 v31, v2
	v_mov_b32_e32 v32, v2
	v_mov_b32_e32 v33, v2
	v_mov_b32_e32 v34, v2
	v_mov_b32_e32 v35, v2
	v_mov_b32_e32 v36, v2
	v_mov_b32_e32 v37, v2
	v_mov_b32_e32 v38, v2
	v_mov_b32_e32 v39, v2
	v_mov_b32_e32 v40, v2
	v_mov_b32_e32 v41, v2
	v_mov_b32_e32 v42, v2
	v_mov_b32_e32 v43, v2
	v_mov_b32_e32 v44, v2
	v_mov_b32_e32 v45, v2
	v_mov_b32_e32 v46, v2
	v_mov_b32_e32 v47, v2
	v_mov_b32_e32 v48, v2
	v_mov_b32_e32 v49, v2
	v_mov_b32_e32 v50, v2
	v_mov_b32_e32 v51, v2
	v_mov_b32_e32 v52, v2
	v_mov_b32_e32 v53, v2
	v_mov_b32_e32 v54, v2
	v_mov_b32_e32 v55, v2
	v_mov_b32_e32 v56, v2
	v_mov_b32_e32 v57, v2
	v_mov_b32_e32 v58, v2
	v_mov_b32_e32 v59, v2
	v_mov_b32_e32 v60, v2
	v_mov_b32_e32 v61, v2
	v_mov_b32_e32 v62, v2
	v_mov_b32_e32 v63, v2
	v_mov_b32_e32 v64, v2
	v_mov_b32_e32 v65, v2
	v_mov_b32_e32 v66, v2
	v_mov_b32_e32 v67, v2
	v_mov_b32_e32 v68, v2
	v_mov_b32_e32 v69, v2
	v_mov_b32_e32 v70, v2
	v_mov_b32_e32 v71, v2
	v_mov_b32_e32 v72, v2
	v_mov_b32_e32 v73, v2
	v_mov_b32_e32 v74, v2
	v_mov_b32_e32 v75, v2
	v_mov_b32_e32 v76, v2
	v_mov_b32_e32 v77, v2
	v_mov_b32_e32 v78, v2
	v_mov_b32_e32 v79, v2
	v_mov_b32_e32 v80, v2
	v_mov_b32_e32 v81, v2
	v_mov_b32_e32 v82, v2
	v_mov_b32_e32 v83, v2
	v_mov_b32_e32 v84, v2
	v_mov_b32_e32 v85, v2
	v_mov_b32_e32 v86, v2
	v_mov_b32_e32 v87, v2
	v_mov_b32_e32 v88, v2
	v_mov_b32_e32 v89, v2
	v_mov_b32_e32 v90, v2
	v_mov_b32_e32 v91, v2
	v_mov_b32_e32 v92, v2
	v_mov_b32_e32 v93, v2
	v_mov_b32_e32 v94, v2
	v_mov_b32_e32 v95, v2
	v_mov_b32_e32 v96, v2
	v_mov_b32_e32 v97, v2
	v_mov_b32_e32 v98, v2
	v_mov_b32_e32 v99, v2
	v_mov_b32_e32 v100, v2
	v_mov_b32_e32 v101, v2
	v_mov_b32_e32 v102, v2
	v_mov_b32_e32 v103, v2
	v_mov_b32_e32 v104, v2
	v_mov_b32_e32 v105, v2
	v_mov_b32_e32 v106, v2
	v_mov_b32_e32 v107, v2
	v_mov_b32_e32 v108, v2
	v_mov_b32_e32 v109, v2
	v_mov_b32_e32 v110, v2
	v_mov_b32_e32 v111, v2
	v_mov_b32_e32 v112, v2
	v_mov_b32_e32 v113, v2
	v_mov_b32_e32 v114, v2
	v_mov_b32_e32 v115, v2
	v_mov_b32_e32 v116, v2
	v_mov_b32_e32 v117, v2
	v_mov_b32_e32 v118, v2
	v_mov_b32_e32 v119, v2
	v_mov_b32_e32 v120, v2
	v_mov_b32_e32 v121, v2
	v_mov_b32_e32 v122, v2
	v_mov_b32_e32 v123, v2
	v_mov_b32_e32 v124, v2
	v_mov_b32_e32 v125, v2
	v_mov_b32_e32 v126, v2
	v_mov_b32_e32 v127, v2
	v_mov_b32_e32 v128, v2
	v_mov_b32_e32 v129, v2
	.p2align	6

; template <int DQK, int MODE> ...
;     ...
;   auto lstore = [&](const TRegs& R, int st) {
;     u16* Ks = lds + st * STG;
;     u16* Vs = Ks + KT;
; #pragma unroll
;     for (int i = 0; i < NKL; ++i) {
;       int c = tid + i * 256;
;       int row = c / KCH, cc = c % KCH;
;       *(u32x4*)(Ks + row * KST + cc * 8) = R.k[i];
;     }
; #pragma unroll
;     for (int i = 0; i < 2; ++i) {
;       int c = tid + i * 256;
;       int d = c >> 3, cc = c & 7;
;       u32x2 lo = {R.v[i].x, R.v[i].y}, hi = {R.v[i].z, R.v[i].w};
;       *(u32x2*)(Vs + d * VST + cc * 8) = lo;
;       *(u32x2*)(Vs + d * VST + cc * 8 + 4) = hi;
;     }
;     ...
;   f32x16 O[2];
; #pragma unroll
;   for (int du = 0; du < 2; ++du)
; #pragma unroll
;     for (int r = 0; r < 16; ++r) O[du][r] = 0.f;
;   float m_run = 0.f, lsum = 0.f;
;   bool first = true;
;   float carry = active ? 1.f : 0.f;
;   const int dir = (MODE == 2) ? -1 : 1;
;   const int jstart = (MODE == 2) ? jhi : jlo;
;   const int ntile = jhi - jlo + 1;
;     ...
;   {
;     TRegs R0, R1;
;     gload(R0, jstart);
;     if (ntile > 1) gload(R1, jstart + dir);
.LBB0_2122:
	v_lshlrev_b32_e32 v174, 3, v13
	v_mov_b32_e32 v47, 0
	s_cmp_lt_i32 s9, 0xfff00000
	v_mov_b32_e32 v46, 0
	v_mov_b32_e32 v45, 0
	v_mov_b32_e32 v44, 0
	v_mov_b32_e32 v43, 0
	v_mov_b32_e32 v42, 0
	v_mov_b32_e32 v41, 0
	v_mov_b32_e32 v40, 0
	v_mov_b32_e32 v39, 0
	v_mov_b32_e32 v38, 0
	v_mov_b32_e32 v37, 0
	v_mov_b32_e32 v36, 0
	v_mov_b32_e32 v35, 0
	v_mov_b32_e32 v34, 0
	v_mov_b32_e32 v33, 0
	v_mov_b32_e32 v32, 0
	v_mov_b32_e32 v31, 0
	v_mov_b32_e32 v30, 0
	v_mov_b32_e32 v29, 0
	v_mov_b32_e32 v28, 0
	v_mov_b32_e32 v27, 0
	v_mov_b32_e32 v26, 0
	v_mov_b32_e32 v25, 0
	v_mov_b32_e32 v24, 0
	v_mov_b32_e32 v23, 0
	v_mov_b32_e32 v22, 0
	v_mov_b32_e32 v21, 0
	v_mov_b32_e32 v20, 0
	v_mov_b32_e32 v19, 0
	v_mov_b32_e32 v18, 0
	v_mov_b32_e32 v17, 0
	v_mov_b32_e32 v16, 0
	v_mov_b32_e32 v175, 0
	s_cbranch_scc1 .LBB0_2139
	v_lshl_add_u64 v[176:177], v[2:3], 1, s[12:13]
	v_ashrrev_i32_e32 v3, 7, v12
	v_cndmask_b32_e64 v3, 0, v3, s[46:47]
	v_add_u32_e32 v197, s14, v3
	v_max_i32_e32 v3, 0x100000, v197
	s_movk_i32 s9, 0xd0
	v_add_u32_e32 v199, 0xfff00000, v3
	v_mul_lo_u32 v3, v169, s9
	v_lshl_add_u32 v200, v2, 1, v3
	v_mul_lo_u32 v2, v171, s9
	v_lshl_add_u32 v201, v4, 1, v2
	v_mul_lo_u32 v2, v173, s9
	v_lshl_add_u32 v202, v8, 1, v2
	v_lshrrev_b32_e32 v2, 3, v12
	v_lshl_add_u64 v[178:179], v[4:5], 1, s[12:13]
	v_lshl_add_u64 v[180:181], v[8:9], 1, s[12:13]
	v_mad_u64_u32 v[182:183], s[12:13], v2, s95, v[0:1]
	v_lshrrev_b32_e32 v2, 3, v14
	v_mad_u64_u32 v[184:185], s[12:13], v2, s95, v[0:1]
	v_lshlrev_b32_e32 v0, 1, v174
	v_mul_u32_u24_e32 v2, 0x68, v170
	v_lshl_add_u32 v183, v2, 1, v0
	v_sub_u32_e32 v0, v0, v174
	v_mul_u32_u24_e32 v2, 0x4c, v170
	s_mov_b32 s9, s19
	v_lshl_add_u32 v185, v2, 1, v0
	s_lshl_b64 s[12:13], s[8:9], 13
	v_and_b32_e32 v0, 7, v12
	v_lshl_or_b32 v2, v0, 4, s12
	v_mov_b32_e32 v3, s13
	v_lshl_add_u64 v[4:5], v[6:7], 1, v[2:3]
	v_lshl_add_u64 v[2:3], v[10:11], 1, v[2:3]
	v_mov_b32_e32 v14, v1
	v_mov_b32_e32 v15, v1
	v_lshl_add_u64 v[186:187], s[10:11], 0, v[4:5]
	v_lshl_add_u64 v[188:189], s[10:11], 0, v[2:3]
	v_mov_b32_e32 v0, v1
	v_mov_b32_e32 v2, v1
	v_mov_b32_e32 v3, v1
	v_mov_b32_e32 v4, v1
	v_mov_b32_e32 v5, v1
	v_mov_b32_e32 v6, v1
	v_mov_b32_e32 v7, v1
	v_mov_b32_e32 v8, v1
	v_mov_b32_e32 v9, v1
	v_mov_b32_e32 v10, v1
	v_mov_b32_e32 v11, v1
	v_mov_b32_e32 v12, v1
	v_mov_b32_e32 v13, v1
	v_mov_b64_e32 v[30:31], v[14:15]
	v_mov_b64_e32 v[46:47], v[14:15]
	s_mov_b32 s17, 3
	s_lshl_b32 s9, s8, 6
	s_mov_b64 s[10:11], -1
	v_mov_b32_e32 v175, 0
	s_xor_b64 s[12:13], vcc, -1
	v_mov_b64_e32 v[28:29], v[12:13]
	v_mov_b64_e32 v[26:27], v[10:11]
	v_mov_b64_e32 v[24:25], v[8:9]
	v_mov_b64_e32 v[22:23], v[6:7]
	v_mov_b64_e32 v[20:21], v[4:5]
	v_mov_b64_e32 v[18:19], v[2:3]
	v_mov_b64_e32 v[16:17], v[0:1]
	v_mov_b64_e32 v[44:45], v[12:13]
	v_mov_b64_e32 v[42:43], v[10:11]
	v_mov_b64_e32 v[40:41], v[8:9]
	v_mov_b64_e32 v[38:39], v[6:7]
	v_mov_b64_e32 v[36:37], v[4:5]
	v_mov_b64_e32 v[34:35], v[2:3]
	v_mov_b64_e32 v[32:33], v[0:1]
	v_mov_b32_e32 v0, 0
	v_mov_b64_e32 v[228:229], 0
	v_mov_b64_e32 v[230:231], 0
	v_mov_b64_e32 v[232:233], 0
	v_mov_b64_e32 v[234:235], 0
	v_mov_b64_e32 v[236:237], 0
	v_mov_b64_e32 v[238:239], 0
	v_mov_b64_e32 v[240:241], 0
	v_mov_b64_e32 v[242:243], 0
	s_waitcnt vmcnt(0)
	v_add_u32_e32 v226, 0x3400, v182
	ds_write_b128 v200, v[104:107]
	ds_write_b128 v201, v[108:111]
	ds_write_b128 v202, v[112:115]
	ds_write2_b64 v226, v[116:117], v[118:119] offset1:1
	v_add_u32_e32 v226, 0x3400, v184
	ds_write2_b64 v226, v[128:129], v[130:131] offset1:1
	s_branch .LBB0_2127
	.p2align	6
